# race-free version: B0 LDS reads moved one phase earlier in the w_up K-loop with an added vmcnt(10) retire wait; conv rewrite; attention K-fragment prefetch
# speedup vs baseline: 1.0220x; 1.0006x over previous
.LBB0_561:
	ds_read_b128 v[64:67], v189 offset:49152
	ds_read_b128 v[68:71], v189 offset:57344
	ds_read_b128 v[210:213], v190 offset:49152
	ds_read_b128 v[218:221], v190 offset:57344
	s_add_i32 s0, 0, 0x12000
	v_add_f32_e32 v148, 0, v175
	s_waitcnt lgkmcnt(3)
	v_mfma_f32_32x32x16_bf16 v[80:95], v[64:67], v[120:123], 0
	v_add_f32_e32 v148, v217, v148
	v_add_f32_e32 v148, v149, v148
	v_add_f32_e32 v148, v216, v148
	v_add_f32_e32 v148, v150, v148
	v_add_f32_e32 v148, v174, v148
	v_add_f32_e32 v148, v151, v148
	v_add_f32_e32 v148, v173, v148
	s_waitcnt lgkmcnt(2)
	v_mfma_f32_32x32x16_bf16 v[64:79], v[68:71], v[120:123], 0
	v_add_f32_e32 v148, v154, v148
	v_add_f32_e32 v148, v172, v148
	v_add_f32_e32 v148, v153, v148
	v_add_f32_e32 v148, v155, v148
	v_exp_f32_e32 v140, v140
	v_add_f32_e32 v148, v145, v148
	v_exp_f32_e32 v141, v141
	s_waitcnt lgkmcnt(1)
	v_mfma_f32_32x32x16_bf16 v[80:95], v[210:213], v[124:127], v[80:95]
	v_add_f32_e32 v148, v147, v148
	v_exp_f32_e32 v138, v138
	v_add_f32_e32 v148, v144, v148
	v_exp_f32_e32 v139, v139
	v_add_f32_e32 v148, v146, v148
	v_exp_f32_e32 v132, v132
	v_add_f32_e32 v148, v140, v148
	s_waitcnt lgkmcnt(0)
	v_mfma_f32_32x32x16_bf16 v[64:79], v[218:221], v[124:127], v[64:79]
	ds_read_b128 v[210:213], v191 offset:49152
	ds_read_b128 v[218:221], v191 offset:57344
	v_exp_f32_e32 v133, v133
	v_add_f32_e32 v148, v141, v148
	v_exp_f32_e32 v130, v130
	v_add_f32_e32 v148, v138, v148
	v_exp_f32_e32 v131, v131
	v_add_f32_e32 v148, v139, v148
	s_waitcnt lgkmcnt(1)
	v_mfma_f32_32x32x16_bf16 v[80:95], v[210:213], v[116:119], v[80:95]
	v_exp_f32_e32 v128, v128
	v_add_f32_e32 v148, v132, v148
	v_exp_f32_e32 v129, v129
	v_add_f32_e32 v148, v133, v148
	v_exp_f32_e32 v142, v142
	v_add_f32_e32 v148, v130, v148
	v_exp_f32_e32 v143, v143
	s_waitcnt lgkmcnt(0)
	v_mfma_f32_32x32x16_bf16 v[64:79], v[218:221], v[116:119], v[64:79]
	ds_read_b128 v[210:213], v192 offset:49152
	ds_read_b128 v[218:221], v192 offset:57344
	v_add_f32_e32 v148, v131, v148
	v_exp_f32_e32 v136, v136
	v_add_f32_e32 v148, v128, v148
	v_exp_f32_e32 v137, v137
	v_add_f32_e32 v148, v129, v148
	v_exp_f32_e32 v134, v134
	s_waitcnt lgkmcnt(1)
	v_mfma_f32_32x32x16_bf16 v[80:95], v[210:213], v[112:115], v[80:95]
	v_add_f32_e32 v148, v142, v148
	v_exp_f32_e32 v135, v135
	v_add_f32_e32 v148, v143, v148
	v_add_f32_e32 v148, v136, v148
	v_add_f32_e32 v148, v137, v148
	v_add_f32_e32 v148, v134, v148
	s_waitcnt lgkmcnt(0)
	v_mfma_f32_32x32x16_bf16 v[64:79], v[218:221], v[112:115], v[64:79]
	ds_read_b128 v[210:213], v193 offset:49152
	ds_read_b128 v[218:221], v193 offset:57344
	ds_read_b128 v[232:235], v194 offset:49152
	ds_read_b128 v[236:239], v194 offset:57344
	s_waitcnt lgkmcnt(3)
	v_mfma_f32_32x32x16_bf16 v[80:95], v[210:213], v[108:111], v[80:95]
	s_waitcnt lgkmcnt(2)
	v_mfma_f32_32x32x16_bf16 v[64:79], v[218:221], v[108:111], v[64:79]
	ds_read_b128 v[210:213], v195 offset:49152
	ds_read_b128 v[218:221], v195 offset:57344
	s_waitcnt lgkmcnt(3)
	v_mfma_f32_32x32x16_bf16 v[80:95], v[232:235], v[104:107], v[80:95]
	s_waitcnt lgkmcnt(2)
	v_mfma_f32_32x32x16_bf16 v[64:79], v[236:239], v[104:107], v[64:79]
	ds_read_b128 v[232:235], v196 offset:49152
	ds_read_b128 v[236:239], v196 offset:57344
	s_waitcnt lgkmcnt(3)
	v_mfma_f32_32x32x16_bf16 v[80:95], v[210:213], v[100:103], v[80:95]
	v_add_u32_e32 v230, s0, v198
	v_add_u32_e32 v231, s0, v200
	s_waitcnt lgkmcnt(2)
	v_mfma_f32_32x32x16_bf16 v[64:79], v[218:221], v[100:103], v[64:79]
	ds_read_b128 v[210:213], v230
	ds_read_b128 v[218:221], v230 offset:4096
	ds_read_b128 v[222:225], v197
	s_waitcnt lgkmcnt(4)
	v_mfma_f32_32x32x16_bf16 v[80:95], v[232:235], v[96:99], v[80:95]
	s_waitcnt lgkmcnt(3)
	v_mfma_f32_32x32x16_bf16 v[64:79], v[236:239], v[96:99], v[64:79]
	ds_read_b128 v[232:235], v231
	ds_read_b128 v[236:239], v231 offset:4096
	ds_read_b128 v[226:229], v184
	s_waitcnt lgkmcnt(3)
	v_mfma_f32_32x32x16_bf16 v[80:95], v[210:213], v[222:225], v[80:95]
	v_mfma_f32_32x32x16_bf16 v[64:79], v[218:221], v[222:225], v[64:79]
	v_add_u32_e32 v244, s0, v202
	v_add_u32_e32 v247, s0, v204
	ds_read_b128 v[210:213], v244
	ds_read_b128 v[218:221], v244 offset:4096
	ds_read_b128 v[222:225], v183
	s_waitcnt lgkmcnt(3)
	v_mfma_f32_32x32x16_bf16 v[80:95], v[232:235], v[226:229], v[80:95]
	v_add_f32_e32 v214, v135, v148
	v_mov_b32_e32 v215, v214
	s_nop 1
	v_permlane32_swap_b32_e32 v214, v215
	v_mfma_f32_32x32x16_bf16 v[64:79], v[236:239], v[226:229], v[64:79]
	ds_read_b128 v[232:235], v247
	ds_read_b128 v[236:239], v247 offset:4096
	ds_read_b128 v[226:229], v182
	s_waitcnt lgkmcnt(3)
	v_mfma_f32_32x32x16_bf16 v[80:95], v[210:213], v[222:225], v[80:95]
	v_mfma_f32_32x32x16_bf16 v[64:79], v[218:221], v[222:225], v[64:79]
	v_cvt_pk_bf16_f32 v148, v175, v217
	v_cvt_pk_bf16_f32 v149, v149, v216
	v_cvt_pk_bf16_f32 v150, v150, v174
	v_cvt_pk_bf16_f32 v151, v151, v173
	v_cvt_pk_bf16_f32 v152, v154, v172
	v_cvt_pk_bf16_f32 v153, v153, v155
	s_waitcnt lgkmcnt(0)
	v_mfma_f32_32x32x16_bf16 v[80:95], v[232:235], v[226:229], v[80:95]
	v_cvt_pk_bf16_f32 v154, v145, v147
	v_permlane32_swap_b32_e32 v148, v150
	v_cvt_pk_bf16_f32 v155, v144, v146
	v_permlane32_swap_b32_e32 v152, v154
	v_cvt_pk_bf16_f32 v216, v140, v141
	v_mfma_f32_32x32x16_bf16 v[64:79], v[236:239], v[226:229], v[64:79]
	v_cvt_pk_bf16_f32 v217, v138, v139
	v_cvt_pk_bf16_f32 v218, v132, v133
	v_cvt_pk_bf16_f32 v219, v130, v131
	v_cvt_pk_bf16_f32 v220, v128, v129
	v_cvt_pk_bf16_f32 v221, v142, v143
	v_cvt_pk_bf16_f32 v222, v136, v137
	v_cvt_pk_bf16_f32 v223, v134, v135
	v_permlane32_swap_b32_e32 v149, v151
	v_permlane32_swap_b32_e32 v153, v155
	v_permlane32_swap_b32_e32 v216, v218
	v_permlane32_swap_b32_e32 v217, v219
	v_permlane32_swap_b32_e32 v220, v222
	v_permlane32_swap_b32_e32 v221, v223
	v_lshl_add_u64 v[172:173], s[64:65], 0, v[158:159]
	s_mov_b32 s0, 0x34e80000
	v_add_co_u32_e32 v132, vcc, s0, v172
	s_mov_b32 s0, 0x34ea0000
	s_nop 0
	v_addc_co_u32_e32 v133, vcc, 0, v173, vcc
	v_add_co_u32_e32 v136, vcc, s0, v172
	v_lshl_add_u64 v[174:175], s[64:65], 0, v[170:171]
	s_nop 0
	v_addc_co_u32_e32 v137, vcc, 0, v173, vcc
	global_load_dwordx4 v[128:131], v[132:133], off offset:256
	s_nop 0
	global_load_dwordx4 v[132:135], v[132:133], off
	s_nop 0
	global_load_dwordx4 v[140:143], v[136:137], off offset:256
	s_nop 0
	global_load_dwordx4 v[136:139], v[136:137], off
	s_mov_b32 s0, 0x1ea04000
	v_add_co_u32_e32 v144, vcc, s0, v174
	s_nop 1
	v_addc_co_u32_e32 v145, vcc, 0, v175, vcc
	global_load_dwordx4 v[144:147], v[144:145], off
	ds_read_b64_tr_b16 v[224:225], v181 offset:0
	ds_read_b64_tr_b16 v[226:227], v181 offset:0x800
	ds_read_b64_tr_b16 v[228:229], v181 offset:0x1000
	ds_read_b64_tr_b16 v[230:231], v181 offset:0x1800
	ds_read_b64_tr_b16 v[232:233], v181 offset:0x2000
	ds_read_b64_tr_b16 v[234:235], v181 offset:0x2800
	ds_read_b64_tr_b16 v[236:237], v181 offset:0x3000
	ds_read_b64_tr_b16 v[238:239], v181 offset:0x3800
	s_waitcnt lgkmcnt(0)
	s_nop 0
	v_mfma_f32_32x32x16_bf16 v[0:15], v[148:151], v[224:227], v[0:15]
	ds_read_b64_tr_b16 v[224:225], v181 offset:0x200
	ds_read_b64_tr_b16 v[226:227], v181 offset:0xa00
	v_mfma_f32_32x32x16_bf16 v[0:15], v[152:155], v[228:231], v[0:15]
	ds_read_b64_tr_b16 v[228:229], v181 offset:0x1200
	ds_read_b64_tr_b16 v[230:231], v181 offset:0x1a00
	v_mfma_f32_32x32x16_bf16 v[0:15], v[216:219], v[232:235], v[0:15]
	ds_read_b64_tr_b16 v[232:233], v181 offset:0x2200
	ds_read_b64_tr_b16 v[234:235], v181 offset:0x2a00
	v_mfma_f32_32x32x16_bf16 v[0:15], v[220:223], v[236:239], v[0:15]
	ds_read_b64_tr_b16 v[236:237], v181 offset:0x3200
	ds_read_b64_tr_b16 v[238:239], v181 offset:0x3a00
	s_waitcnt lgkmcnt(0)
	v_mfma_f32_32x32x16_bf16 v[48:63], v[148:151], v[224:227], v[48:63]
	ds_read_b64_tr_b16 v[224:225], v181 offset:0x400
	ds_read_b64_tr_b16 v[226:227], v181 offset:0xc00
	v_mfma_f32_32x32x16_bf16 v[48:63], v[152:155], v[228:231], v[48:63]
	ds_read_b64_tr_b16 v[228:229], v181 offset:0x1400
	ds_read_b64_tr_b16 v[230:231], v181 offset:0x1c00
	v_mfma_f32_32x32x16_bf16 v[48:63], v[216:219], v[232:235], v[48:63]
	ds_read_b64_tr_b16 v[232:233], v181 offset:0x2400
	ds_read_b64_tr_b16 v[234:235], v181 offset:0x2c00
	v_mfma_f32_32x32x16_bf16 v[48:63], v[220:223], v[236:239], v[48:63]
	ds_read_b64_tr_b16 v[236:237], v181 offset:0x3400
	ds_read_b64_tr_b16 v[238:239], v181 offset:0x3c00
	s_waitcnt lgkmcnt(0)
	v_mfma_f32_32x32x16_bf16 v[32:47], v[148:151], v[224:227], v[32:47]
	ds_read_b64_tr_b16 v[224:225], v181 offset:0x600
	ds_read_b64_tr_b16 v[226:227], v181 offset:0xe00
	v_mfma_f32_32x32x16_bf16 v[32:47], v[152:155], v[228:231], v[32:47]
	ds_read_b64_tr_b16 v[228:229], v181 offset:0x1600
	ds_read_b64_tr_b16 v[230:231], v181 offset:0x1e00
	v_mfma_f32_32x32x16_bf16 v[32:47], v[216:219], v[232:235], v[32:47]
	ds_read_b64_tr_b16 v[232:233], v181 offset:0x2600
	ds_read_b64_tr_b16 v[234:235], v181 offset:0x2e00
	v_mfma_f32_32x32x16_bf16 v[32:47], v[220:223], v[236:239], v[32:47]
	ds_read_b64_tr_b16 v[236:237], v181 offset:0x3600
	ds_read_b64_tr_b16 v[238:239], v181 offset:0x3e00
	s_waitcnt lgkmcnt(0)
	v_mfma_f32_32x32x16_bf16 v[16:31], v[148:151], v[224:227], v[16:31]
	v_max_f32_e32 v148, v81, v81
	v_max_f32_e32 v149, v80, v80
	v_max_f32_e32 v148, v149, v148
	v_max3_f32 v148, v148, v82, v83
	v_max3_f32 v148, v148, v84, v85
	v_max3_f32 v148, v148, v86, v87
	v_max3_f32 v148, v148, v88, v89
	v_max3_f32 v148, v148, v90, v91
	v_max3_f32 v148, v148, v92, v93
	v_mfma_f32_32x32x16_bf16 v[16:31], v[152:155], v[228:231], v[16:31]
	v_max3_f32 v148, v148, v94, v95
	v_max3_f32 v148, v148, v64, v65
	v_max3_f32 v148, v148, v66, v67
	v_max3_f32 v148, v148, v68, v69
	v_max3_f32 v148, v148, v70, v71
	v_max3_f32 v148, v148, v72, v73
	v_max3_f32 v148, v148, v74, v75
	v_max3_f32 v148, v148, v76, v77
	v_mfma_f32_32x32x16_bf16 v[16:31], v[216:219], v[232:235], v[16:31]
	v_max3_f32 v148, v148, v78, v79
	v_mov_b32_e32 v149, v148
	s_nop 1
	v_permlane32_swap_b32_e32 v148, v149
	v_max_f32_e32 v149, v149, v149
	v_max_f32_e32 v148, v148, v148
	v_max_f32_e32 v148, v148, v149
	v_sub_f32_e32 v149, v148, v209
	v_cmp_ge_f32_e32 vcc, s90, v149
	v_max_f32_e32 v149, v209, v209
	v_max_f32_e32 v148, v149, v148
	v_mfma_f32_32x32x16_bf16 v[16:31], v[220:223], v[236:239], v[16:31]
	v_sub_f32_e32 v149, v209, v148
	v_mul_f32_e32 v149, 0x3dd53b94, v149
	v_exp_f32_e32 v149, v149
	s_cmp_eq_u64 vcc, exec
	s_cselect_b64 s[6:7], -1, 0
	s_barrier
	s_waitcnt vmcnt(0)
	v_cndmask_b32_e64 v152, v149, 1.0, s[6:7]
	s_waitcnt vmcnt(4)
	ds_write_b128 v185, v[128:131]
	s_waitcnt vmcnt(2)
	ds_write_b128 v186, v[140:143]
	ds_write_b128 v187, v[132:135] offset:32768
	s_waitcnt vmcnt(1)
	ds_write_b128 v188, v[136:139] offset:32768
	v_add_u32_e32 v128, 0x10000, v207
	v_cmp_gt_f32_e32 vcc, 1.0, v152
	s_waitcnt vmcnt(0)
	ds_write_b128 v128, v[144:147]
	s_cbranch_vccz .LBB0_565
	s_and_saveexec_b64 s[0:1], s[4:5]
	ds_write_b32 v178, v152 offset:128
	s_or_b64 exec, exec, s[0:1]
	s_waitcnt lgkmcnt(0)
	v_add_u32_e32 v140, v157, v160
	ds_read_b128 v[128:131], v140 offset:224
	ds_read_b128 v[132:135], v140 offset:192
	ds_read_b128 v[136:139], v140 offset:160
	ds_read_b128 v[140:143], v140 offset:128
	s_waitcnt lgkmcnt(3)
	v_pk_mul_f32 v[12:13], v[12:13], v[128:129]
	s_waitcnt lgkmcnt(2)
	v_pk_mul_f32 v[8:9], v[8:9], v[132:133]
	s_waitcnt lgkmcnt(1)
	v_pk_mul_f32 v[4:5], v[4:5], v[136:137]
	v_pk_mul_f32 v[14:15], v[14:15], v[130:131]
	v_pk_mul_f32 v[10:11], v[10:11], v[134:135]
	v_pk_mul_f32 v[6:7], v[6:7], v[138:139]
	s_waitcnt lgkmcnt(0)
	v_pk_mul_f32 v[2:3], v[2:3], v[142:143]
	v_pk_mul_f32 v[0:1], v[0:1], v[140:141]
	v_pk_mul_f32 v[60:61], v[60:61], v[128:129]
	v_pk_mul_f32 v[56:57], v[56:57], v[132:133]
	v_pk_mul_f32 v[52:53], v[52:53], v[136:137]
	v_pk_mul_f32 v[62:63], v[62:63], v[130:131]
	v_pk_mul_f32 v[58:59], v[58:59], v[134:135]
	v_pk_mul_f32 v[54:55], v[54:55], v[138:139]
	v_pk_mul_f32 v[50:51], v[50:51], v[142:143]
	v_pk_mul_f32 v[48:49], v[48:49], v[140:141]
	v_pk_mul_f32 v[44:45], v[44:45], v[128:129]
	v_pk_mul_f32 v[40:41], v[40:41], v[132:133]
	v_pk_mul_f32 v[36:37], v[36:37], v[136:137]
	v_pk_mul_f32 v[46:47], v[46:47], v[130:131]
	v_pk_mul_f32 v[42:43], v[42:43], v[134:135]
	v_pk_mul_f32 v[38:39], v[38:39], v[138:139]
	v_pk_mul_f32 v[34:35], v[34:35], v[142:143]
	v_pk_mul_f32 v[32:33], v[32:33], v[140:141]
	v_pk_mul_f32 v[28:29], v[28:29], v[128:129]
	v_pk_mul_f32 v[24:25], v[24:25], v[132:133]
	v_pk_mul_f32 v[20:21], v[20:21], v[136:137]
	v_pk_mul_f32 v[30:31], v[30:31], v[130:131]
	v_pk_mul_f32 v[26:27], v[26:27], v[134:135]
	v_pk_mul_f32 v[22:23], v[22:23], v[138:139]
	v_pk_mul_f32 v[18:19], v[18:19], v[142:143]
	v_pk_mul_f32 v[16:17], v[16:17], v[140:141]

.LBB0_1056:
	s_add_u32 s0, s78, 0xfff80080
	s_addc_u32 s1, s79, -1
	s_add_i32 s50, 0, 0x10000
	v_add_u32_e32 v76, s50, v205
	ds_read_b128 v[64:67], v76
	ds_read_b128 v[68:71], v76 offset:1024
	ds_read_b128 v[72:75], v76 offset:2048
	ds_read_b128 v[76:79], v76 offset:3072
	s_cmp_eq_u32 s47, 28
	s_cselect_b32 s81, s14, s1
	s_cselect_b32 s80, s15, s0
	s_cselect_b32 s1, s16, s13
	s_cselect_b32 s0, s17, s12
	ds_read_b128 v[80:83], v207
	ds_read_b128 v[84:87], v207 offset:1024
	ds_read_b128 v[88:91], v207 offset:2048
	ds_read_b128 v[92:95], v207 offset:3072
	ds_read_b128 v[180:183], v207 offset:4096
	ds_read_b128 v[184:187], v207 offset:5120
	ds_read_b128 v[188:191], v207 offset:6144
	ds_read_b128 v[192:195], v207 offset:7168
	s_waitcnt lgkmcnt(8)
	s_barrier
	s_waitcnt lgkmcnt(0)
	s_waitcnt lgkmcnt(0)
	v_mfma_f32_16x16x32_bf16 v[156:159], v[64:67], v[80:83], v[156:159]
	v_mfma_f32_16x16x32_bf16 v[152:155], v[72:75], v[80:83], v[152:155]
	v_mfma_f32_16x16x32_bf16 v[148:151], v[64:67], v[88:91], v[148:151]
	v_mfma_f32_16x16x32_bf16 v[140:143], v[72:75], v[88:91], v[140:143]
	v_mfma_f32_16x16x32_bf16 v[132:135], v[64:67], v[180:183], v[132:135]
	v_mfma_f32_16x16x32_bf16 v[124:127], v[72:75], v[180:183], v[124:127]
	v_mfma_f32_16x16x32_bf16 v[116:119], v[64:67], v[188:191], v[116:119]
	v_mfma_f32_16x16x32_bf16 v[108:111], v[72:75], v[188:191], v[108:111]
	v_mfma_f32_16x16x32_bf16 v[156:159], v[68:71], v[84:87], v[156:159]
	v_mfma_f32_16x16x32_bf16 v[152:155], v[76:79], v[84:87], v[152:155]
	v_mfma_f32_16x16x32_bf16 v[148:151], v[68:71], v[92:95], v[148:151]
	v_mfma_f32_16x16x32_bf16 v[140:143], v[76:79], v[92:95], v[140:143]
	v_mfma_f32_16x16x32_bf16 v[132:135], v[68:71], v[184:187], v[132:135]
	v_mfma_f32_16x16x32_bf16 v[124:127], v[76:79], v[184:187], v[124:127]
	v_mfma_f32_16x16x32_bf16 v[116:119], v[68:71], v[192:195], v[116:119]
	v_mfma_f32_16x16x32_bf16 v[108:111], v[76:79], v[192:195], v[108:111]
	s_barrier
	v_lshl_add_u64 v[196:197], s[78:79], 0, v[176:177]
	s_add_i32 m0, s22, 0xc000
	s_nop 0
	global_load_lds_dwordx4 v[196:197], off
	v_lshl_add_u64 v[196:197], s[78:79], 0, v[178:179]
	s_add_i32 m0, s22, 0xe000
	s_nop 0
	global_load_lds_dwordx4 v[196:197], off
	s_add_i32 s66, 0, 0x14000
	s_add_i32 s50, s50, s21
	v_add_u32_e32 v212, s66, v205
	v_lshl_add_u64 v[224:225], s[0:1], 0, v[160:161]
	s_mov_b32 m0, s50
	ds_read_b128 v[196:199], v212
	ds_read_b128 v[200:203], v212 offset:1024
	ds_read_b128 v[208:211], v212 offset:2048
	ds_read_b128 v[212:215], v212 offset:3072
	global_load_lds_dwordx4 v[224:225], off
	v_lshl_add_u64 v[226:227], s[0:1], 0, v[170:171]
	s_add_i32 m0, s50, 0x2000
	s_nop 0
	global_load_lds_dwordx4 v[226:227], off
	s_barrier
	s_waitcnt lgkmcnt(0)
	s_waitcnt lgkmcnt(0)
	v_mfma_f32_16x16x32_bf16 v[144:147], v[196:199], v[80:83], v[144:147]
	v_mfma_f32_16x16x32_bf16 v[80:83], v[208:211], v[80:83], v[136:139]
	v_mfma_f32_16x16x32_bf16 v[144:147], v[200:203], v[84:87], v[144:147]
	v_mfma_f32_16x16x32_bf16 v[80:83], v[212:215], v[84:87], v[80:83]
	v_mfma_f32_16x16x32_bf16 v[84:87], v[196:199], v[88:91], v[128:131]
	v_mfma_f32_16x16x32_bf16 v[88:91], v[208:211], v[88:91], v[120:123]
	v_mfma_f32_16x16x32_bf16 v[104:107], v[208:211], v[180:183], v[104:107]
	v_mfma_f32_16x16x32_bf16 v[100:103], v[196:199], v[188:191], v[100:103]
	v_mfma_f32_16x16x32_bf16 v[96:99], v[208:211], v[188:191], v[96:99]
	v_mfma_f32_16x16x32_bf16 v[84:87], v[200:203], v[92:95], v[84:87]
	v_mfma_f32_16x16x32_bf16 v[88:91], v[212:215], v[92:95], v[88:91]
	v_mfma_f32_16x16x32_bf16 v[92:95], v[196:199], v[180:183], v[112:115]
	v_mfma_f32_16x16x32_bf16 v[104:107], v[212:215], v[184:187], v[104:107]
	v_mfma_f32_16x16x32_bf16 v[100:103], v[200:203], v[192:195], v[100:103]
	v_mfma_f32_16x16x32_bf16 v[96:99], v[212:215], v[192:195], v[96:99]
	v_mfma_f32_16x16x32_bf16 v[92:95], v[200:203], v[184:187], v[92:95]
	s_mov_b32 m0, s22
	v_lshl_add_u64 v[228:229], s[80:81], 0, v[174:175]
	s_barrier
	ds_read_b128 v[112:115], v207 offset:16384
	ds_read_b128 v[120:123], v207 offset:17408
	ds_read_b128 v[128:131], v207 offset:18432
	ds_read_b128 v[136:139], v207 offset:19456
	ds_read_b128 v[180:183], v207 offset:20480
	ds_read_b128 v[184:187], v207 offset:21504
	ds_read_b128 v[188:191], v207 offset:22528
	ds_read_b128 v[192:195], v207 offset:23552
	global_load_lds_dwordx4 v[228:229], off
	v_lshl_add_u64 v[230:231], s[80:81], 0, v[172:173]
	s_mov_b32 m0, s23
	s_nop 0
	global_load_lds_dwordx4 v[230:231], off
	s_waitcnt vmcnt(10)
	s_barrier
	s_waitcnt lgkmcnt(0)
	s_waitcnt lgkmcnt(0)
	v_mfma_f32_16x16x32_bf16 v[60:63], v[64:67], v[112:115], v[60:63]
	v_mfma_f32_16x16x32_bf16 v[56:59], v[72:75], v[112:115], v[56:59]
	v_mfma_f32_16x16x32_bf16 v[44:47], v[64:67], v[128:131], v[44:47]
	v_mfma_f32_16x16x32_bf16 v[40:43], v[72:75], v[128:131], v[40:43]
	v_mfma_f32_16x16x32_bf16 v[28:31], v[64:67], v[180:183], v[28:31]
	v_mfma_f32_16x16x32_bf16 v[24:27], v[72:75], v[180:183], v[24:27]
	v_mfma_f32_16x16x32_bf16 v[12:15], v[64:67], v[188:191], v[12:15]
	v_mfma_f32_16x16x32_bf16 v[8:11], v[72:75], v[188:191], v[8:11]
	v_mfma_f32_16x16x32_bf16 v[60:63], v[68:71], v[120:123], v[60:63]
	v_mfma_f32_16x16x32_bf16 v[56:59], v[76:79], v[120:123], v[56:59]
	v_mfma_f32_16x16x32_bf16 v[44:47], v[68:71], v[136:139], v[44:47]
	v_mfma_f32_16x16x32_bf16 v[40:43], v[76:79], v[136:139], v[40:43]
	v_mfma_f32_16x16x32_bf16 v[28:31], v[68:71], v[184:187], v[28:31]
	v_mfma_f32_16x16x32_bf16 v[24:27], v[76:79], v[184:187], v[24:27]
	v_mfma_f32_16x16x32_bf16 v[12:15], v[68:71], v[192:195], v[12:15]
	v_mfma_f32_16x16x32_bf16 v[8:11], v[76:79], v[192:195], v[8:11]
	s_barrier
	s_add_u32 s50, s0, 0x80000
	s_addc_u32 s51, s1, 0
	s_add_i32 s66, s66, s21
	v_lshl_add_u64 v[64:65], s[50:51], 0, v[160:161]
	s_mov_b32 m0, s66
	s_nop 0
	global_load_lds_dwordx4 v[64:65], off
	v_lshl_add_u64 v[64:65], s[50:51], 0, v[170:171]
	s_add_i32 m0, s66, 0x2000
	s_nop 0
	global_load_lds_dwordx4 v[64:65], off
	v_add_u32_e32 v76, 0x18000, v205
	ds_read_b128 v[64:67], v76
	ds_read_b128 v[68:71], v76 offset:1024
	ds_read_b128 v[72:75], v76 offset:2048
	ds_read_b128 v[76:79], v76 offset:3072
	s_waitcnt vmcnt(6)
	s_barrier
	v_mfma_f32_16x16x32_bf16 v[52:55], v[196:199], v[112:115], v[52:55]
	v_mfma_f32_16x16x32_bf16 v[48:51], v[208:211], v[112:115], v[48:51]
	v_mfma_f32_16x16x32_bf16 v[36:39], v[196:199], v[128:131], v[36:39]
	v_mfma_f32_16x16x32_bf16 v[32:35], v[208:211], v[128:131], v[32:35]
	v_mfma_f32_16x16x32_bf16 v[20:23], v[196:199], v[180:183], v[20:23]
	v_mfma_f32_16x16x32_bf16 v[16:19], v[208:211], v[180:183], v[16:19]
	v_mfma_f32_16x16x32_bf16 v[4:7], v[196:199], v[188:191], v[4:7]
	v_mfma_f32_16x16x32_bf16 v[0:3], v[208:211], v[188:191], v[0:3]
	v_mfma_f32_16x16x32_bf16 v[52:55], v[200:203], v[120:123], v[52:55]
	v_mfma_f32_16x16x32_bf16 v[48:51], v[212:215], v[120:123], v[48:51]
	v_mfma_f32_16x16x32_bf16 v[36:39], v[200:203], v[136:139], v[36:39]
	v_mfma_f32_16x16x32_bf16 v[32:35], v[212:215], v[136:139], v[32:35]
	v_mfma_f32_16x16x32_bf16 v[20:23], v[200:203], v[184:187], v[20:23]
	v_mfma_f32_16x16x32_bf16 v[16:19], v[212:215], v[184:187], v[16:19]
	v_mfma_f32_16x16x32_bf16 v[4:7], v[200:203], v[192:195], v[4:7]
	v_mfma_f32_16x16x32_bf16 v[0:3], v[212:215], v[192:195], v[0:3]
	s_add_i32 s66, 0, 0x18000
	s_barrier
	ds_read_b128 v[112:115], v207 offset:32768
	ds_read_b128 v[120:123], v207 offset:33792
	ds_read_b128 v[180:183], v207 offset:34816
	ds_read_b128 v[184:187], v207 offset:35840
	ds_read_b128 v[188:191], v207 offset:36864
	ds_read_b128 v[192:195], v207 offset:37888
	ds_read_b128 v[196:199], v207 offset:38912
	ds_read_b128 v[200:203], v207 offset:39936
	s_waitcnt lgkmcnt(8)
	s_barrier
	s_waitcnt lgkmcnt(0)
	s_waitcnt lgkmcnt(0)
	v_mfma_f32_16x16x32_bf16 v[128:131], v[64:67], v[112:115], v[156:159]
	v_mfma_f32_16x16x32_bf16 v[156:159], v[68:71], v[120:123], v[128:131]
	v_mfma_f32_16x16x32_bf16 v[128:131], v[72:75], v[112:115], v[152:155]
	v_mfma_f32_16x16x32_bf16 v[152:155], v[76:79], v[120:123], v[128:131]
	v_mfma_f32_16x16x32_bf16 v[128:131], v[64:67], v[180:183], v[148:151]
	v_mfma_f32_16x16x32_bf16 v[148:151], v[68:71], v[184:187], v[128:131]
	v_mfma_f32_16x16x32_bf16 v[128:131], v[72:75], v[180:183], v[140:143]
	v_mfma_f32_16x16x32_bf16 v[140:143], v[76:79], v[184:187], v[128:131]
	v_mfma_f32_16x16x32_bf16 v[128:131], v[64:67], v[188:191], v[132:135]
	v_mfma_f32_16x16x32_bf16 v[124:127], v[72:75], v[188:191], v[124:127]
	v_mfma_f32_16x16x32_bf16 v[116:119], v[64:67], v[196:199], v[116:119]
	v_mfma_f32_16x16x32_bf16 v[108:111], v[72:75], v[196:199], v[108:111]
	v_mfma_f32_16x16x32_bf16 v[132:135], v[68:71], v[192:195], v[128:131]
	v_mfma_f32_16x16x32_bf16 v[124:127], v[76:79], v[192:195], v[124:127]
	v_mfma_f32_16x16x32_bf16 v[116:119], v[68:71], v[200:203], v[116:119]
	v_mfma_f32_16x16x32_bf16 v[108:111], v[76:79], v[200:203], v[108:111]
	s_barrier
	s_add_u32 s50, s80, 0x80000
	s_addc_u32 s51, s81, 0
	v_lshl_add_u64 v[128:129], s[50:51], 0, v[174:175]
	s_mov_b32 m0, s24
	s_nop 0
	global_load_lds_dwordx4 v[128:129], off
	v_lshl_add_u64 v[128:129], s[50:51], 0, v[172:173]
	s_mov_b32 m0, s25
	s_nop 0
	global_load_lds_dwordx4 v[128:129], off
	s_add_i32 s50, 0, 0x1c000
	v_add_u32_e32 v128, s50, v205
	s_add_i32 s51, s66, s21
	ds_read_b128 v[208:211], v128
	ds_read_b128 v[212:215], v128 offset:1024
	ds_read_b128 v[216:219], v128 offset:2048
	ds_read_b128 v[220:223], v128 offset:3072
	v_lshl_add_u64 v[128:129], v[224:225], 0, s[92:93]
	s_mov_b32 m0, s51
	s_nop 0
	global_load_lds_dwordx4 v[128:129], off
	v_lshl_add_u64 v[128:129], v[226:227], 0, s[92:93]
	s_add_i32 m0, s51, 0x2000
	s_nop 0
	global_load_lds_dwordx4 v[128:129], off
	s_barrier
	s_waitcnt lgkmcnt(0)
	s_waitcnt lgkmcnt(0)
	v_mfma_f32_16x16x32_bf16 v[80:83], v[216:219], v[112:115], v[80:83]
	v_mfma_f32_16x16x32_bf16 v[128:131], v[208:211], v[112:115], v[144:147]
	v_mfma_f32_16x16x32_bf16 v[136:139], v[220:223], v[120:123], v[80:83]
	v_mfma_f32_16x16x32_bf16 v[80:83], v[208:211], v[180:183], v[84:87]
	v_mfma_f32_16x16x32_bf16 v[144:147], v[212:215], v[120:123], v[128:131]
	v_mfma_f32_16x16x32_bf16 v[128:131], v[212:215], v[184:187], v[80:83]
	v_mfma_f32_16x16x32_bf16 v[80:83], v[216:219], v[180:183], v[88:91]
	v_mfma_f32_16x16x32_bf16 v[120:123], v[220:223], v[184:187], v[80:83]
	v_mfma_f32_16x16x32_bf16 v[80:83], v[208:211], v[188:191], v[92:95]
	v_mfma_f32_16x16x32_bf16 v[112:115], v[212:215], v[192:195], v[80:83]
	v_mfma_f32_16x16x32_bf16 v[80:83], v[216:219], v[188:191], v[104:107]
	v_mfma_f32_16x16x32_bf16 v[104:107], v[220:223], v[192:195], v[80:83]
	v_mfma_f32_16x16x32_bf16 v[80:83], v[208:211], v[196:199], v[100:103]
	v_mfma_f32_16x16x32_bf16 v[100:103], v[212:215], v[200:203], v[80:83]
	v_mfma_f32_16x16x32_bf16 v[80:83], v[216:219], v[196:199], v[96:99]
	v_mfma_f32_16x16x32_bf16 v[96:99], v[220:223], v[200:203], v[80:83]
	s_mov_b32 m0, s26
	v_lshl_add_u64 v[196:197], v[228:229], 0, s[92:93]
	s_barrier
	s_nop 2
	ds_read_b128 v[80:83], v207 offset:49152
	ds_read_b128 v[84:87], v207 offset:50176
	ds_read_b128 v[88:91], v207 offset:51200
	ds_read_b128 v[92:95], v207 offset:52224
	ds_read_b128 v[180:183], v207 offset:53248
	ds_read_b128 v[184:187], v207 offset:54272
	ds_read_b128 v[188:191], v207 offset:55296
	ds_read_b128 v[192:195], v207 offset:56320
	global_load_lds_dwordx4 v[196:197], off
	v_lshl_add_u64 v[196:197], v[230:231], 0, s[92:93]
	s_mov_b32 m0, s27
	s_nop 0
	global_load_lds_dwordx4 v[196:197], off
	s_barrier
	s_waitcnt lgkmcnt(0)
	s_waitcnt lgkmcnt(0)
	v_mfma_f32_16x16x32_bf16 v[60:63], v[64:67], v[80:83], v[60:63]
	v_mfma_f32_16x16x32_bf16 v[56:59], v[72:75], v[80:83], v[56:59]
	v_mfma_f32_16x16x32_bf16 v[44:47], v[64:67], v[88:91], v[44:47]
	v_mfma_f32_16x16x32_bf16 v[40:43], v[72:75], v[88:91], v[40:43]
	v_mfma_f32_16x16x32_bf16 v[28:31], v[64:67], v[180:183], v[28:31]
	v_mfma_f32_16x16x32_bf16 v[24:27], v[72:75], v[180:183], v[24:27]
	v_mfma_f32_16x16x32_bf16 v[12:15], v[64:67], v[188:191], v[12:15]
	v_mfma_f32_16x16x32_bf16 v[8:11], v[72:75], v[188:191], v[8:11]
	v_mfma_f32_16x16x32_bf16 v[60:63], v[68:71], v[84:87], v[60:63]
	v_mfma_f32_16x16x32_bf16 v[56:59], v[76:79], v[84:87], v[56:59]
	v_mfma_f32_16x16x32_bf16 v[44:47], v[68:71], v[92:95], v[44:47]
	v_mfma_f32_16x16x32_bf16 v[40:43], v[76:79], v[92:95], v[40:43]
	v_mfma_f32_16x16x32_bf16 v[28:31], v[68:71], v[184:187], v[28:31]
	v_mfma_f32_16x16x32_bf16 v[24:27], v[76:79], v[184:187], v[24:27]
	v_mfma_f32_16x16x32_bf16 v[12:15], v[68:71], v[192:195], v[12:15]
	v_mfma_f32_16x16x32_bf16 v[8:11], v[76:79], v[192:195], v[8:11]
	s_barrier
	s_add_u32 s0, s0, 0x80080
	s_addc_u32 s1, s1, 0
	s_add_i32 s50, s50, s21
	v_lshl_add_u64 v[64:65], s[0:1], 0, v[160:161]
	s_mov_b32 m0, s50
	s_nop 0
	global_load_lds_dwordx4 v[64:65], off
	v_lshl_add_u64 v[64:65], s[0:1], 0, v[170:171]
	s_add_i32 m0, s50, 0x2000
	s_nop 0
	global_load_lds_dwordx4 v[64:65], off
	s_waitcnt vmcnt(6)
	s_barrier
	v_mfma_f32_16x16x32_bf16 v[52:55], v[208:211], v[80:83], v[52:55]
	v_mfma_f32_16x16x32_bf16 v[48:51], v[216:219], v[80:83], v[48:51]
	v_mfma_f32_16x16x32_bf16 v[36:39], v[208:211], v[88:91], v[36:39]
	v_mfma_f32_16x16x32_bf16 v[32:35], v[216:219], v[88:91], v[32:35]
	v_mfma_f32_16x16x32_bf16 v[20:23], v[208:211], v[180:183], v[20:23]
	v_mfma_f32_16x16x32_bf16 v[16:19], v[216:219], v[180:183], v[16:19]
	v_mfma_f32_16x16x32_bf16 v[4:7], v[208:211], v[188:191], v[4:7]
	v_mfma_f32_16x16x32_bf16 v[0:3], v[216:219], v[188:191], v[0:3]
	v_mfma_f32_16x16x32_bf16 v[52:55], v[212:215], v[84:87], v[52:55]
	v_mfma_f32_16x16x32_bf16 v[48:51], v[220:223], v[84:87], v[48:51]
	v_mfma_f32_16x16x32_bf16 v[36:39], v[212:215], v[92:95], v[36:39]
	v_mfma_f32_16x16x32_bf16 v[32:35], v[220:223], v[92:95], v[32:35]
	v_mfma_f32_16x16x32_bf16 v[20:23], v[212:215], v[184:187], v[20:23]
	v_mfma_f32_16x16x32_bf16 v[16:19], v[220:223], v[184:187], v[16:19]
	v_mfma_f32_16x16x32_bf16 v[4:7], v[212:215], v[192:195], v[4:7]
	v_mfma_f32_16x16x32_bf16 v[0:3], v[220:223], v[192:195], v[0:3]
	s_add_i32 s47, s47, 2
	s_add_u32 s78, s78, 0x100
	s_addc_u32 s79, s79, 0
	s_add_u32 s12, s12, 0x100
	s_addc_u32 s13, s13, 0
	s_cmp_gt_u32 s47, 29
	s_barrier
	s_cbranch_scc0 .LBB0_1056
	v_lshl_or_b32 v182, s48, 8, v206
	v_ashrrev_i32_e32 v183, 31, v182
	v_lshlrev_b64 v[64:65], 2, v[182:183]
	v_lshl_add_u64 v[66:67], s[44:45], 0, v[64:65]
	v_lshl_add_u64 v[64:65], s[42:43], 0, v[64:65]
	global_load_dwordx4 v[72:75], v[66:67], off offset:16
	global_load_dwordx4 v[92:95], v[66:67], off
	global_load_dwordx4 v[68:71], v[64:65], off offset:16
	global_load_dwordx4 v[88:91], v[64:65], off
	v_or_b32_e32 v64, 0x80, v182
	v_lshl_add_u32 v180, s49, 8, v204
	v_ashrrev_i32_e32 v65, 31, v64
	v_or_b32_e32 v84, 0x84, v182
	v_lshlrev_b64 v[64:65], 2, v[64:65]
	v_ashrrev_i32_e32 v85, 31, v84
	v_ashrrev_i32_e32 v181, 31, v180
	v_lshl_add_u64 v[66:67], s[44:45], 0, v[64:65]
	v_lshl_add_u64 v[76:77], s[42:43], 0, v[64:65]
	v_lshl_add_u64 v[84:85], v[84:85], 2, s[44:45]
	v_lshl_add_u64 v[202:203], v[180:181], 3, s[8:9]
	global_load_dwordx4 v[80:83], v[66:67], off
	s_nop 0
	global_load_dwordx4 v[64:67], v[76:77], off offset:16
	s_nop 0
	global_load_dwordx4 v[76:79], v[76:77], off
	v_add_co_u32_e32 v200, vcc, s89, v202
	global_load_dwordx4 v[84:87], v[84:85], off
	s_nop 0
	v_addc_co_u32_e32 v201, vcc, 0, v203, vcc
	global_load_dwordx2 v[184:185], v[202:203], off
	global_load_dwordx2 v[186:187], v[200:201], off
	global_load_dwordx2 v[208:209], v[202:203], off offset:128
	global_load_dwordx2 v[210:211], v[200:201], off offset:128
	global_load_dwordx2 v[212:213], v[202:203], off offset:256
	global_load_dwordx2 v[214:215], v[200:201], off offset:256
	global_load_dwordx2 v[216:217], v[202:203], off offset:384
	global_load_dwordx2 v[218:219], v[200:201], off offset:384
	s_mov_b64 s[0:1], 0x200000
	v_readlane_b32 s66, v255, 7
	s_mov_b32 s48, s72
	s_mov_b32 s49, s46
	s_mov_b64 s[12:13], s[74:75]
	v_readlane_b32 s67, v255, 8
	s_waitcnt vmcnt(0)
	v_xor_b32_e32 v197, 0x80000000, v75
	v_xor_b32_e32 v196, 0x80000000, v74
	v_xor_b32_e32 v199, 0x80000000, v95
	v_xor_b32_e32 v198, 0x80000000, v94
	v_xor_b32_e32 v195, 0x80000000, v83
	v_xor_b32_e32 v194, 0x80000000, v82
	v_cvt_f32_u32_e32 v188, v186
	v_xor_b32_e32 v193, 0x80000000, v87
	v_xor_b32_e32 v192, 0x80000000, v86
	v_cvt_f32_u32_e32 v189, v184
	v_cvt_f32_i32_e32 v184, v187
	v_cvt_f32_i32_e32 v185, v185
	v_pk_fma_f32 v[184:185], v[188:189], s[88:89], v[184:185] op_sel_hi:[1,0,1]
	s_nop 0
	v_pk_mul_f32 v[220:221], v[184:185], s[94:95] op_sel_hi:[1,0]
	s_nop 0
	v_fma_f32 v184, -v221, v221, v220
	v_add_f32_e32 v184, 0x3727c5ac, v184
	v_rsq_f32_e32 v222, v184
	v_pk_fma_f32 v[74:75], v[196:197], v[220:221], v[154:155] op_sel:[0,1,0]
	v_pk_fma_f32 v[156:157], v[92:93], v[220:221], v[156:157] op_sel:[0,1,0] neg_lo:[1,0,0] neg_hi:[1,0,0]
	v_pk_fma_f32 v[94:95], v[198:199], v[220:221], v[158:159] op_sel:[0,1,0]
	v_pk_fma_f32 v[186:187], v[74:75], v[222:223], v[70:71] op_sel_hi:[1,0,1]
	v_pk_fma_f32 v[74:75], v[80:81], v[220:221], v[144:145] op_sel:[0,1,0] neg_lo:[1,0,0] neg_hi:[1,0,0]
	v_pk_fma_f32 v[82:83], v[194:195], v[220:221], v[146:147] op_sel:[0,1,0]
	v_pk_fma_f32 v[184:185], v[94:95], v[222:223], v[90:91] op_sel_hi:[1,0,1]
	v_pk_fma_f32 v[188:189], v[156:157], v[222:223], v[88:89] op_sel_hi:[1,0,1]
	v_pk_fma_f32 v[94:95], v[72:73], v[220:221], v[152:153] op_sel:[0,1,0] neg_lo:[1,0,0] neg_hi:[1,0,0]
	v_pk_fma_f32 v[152:153], v[82:83], v[222:223], v[78:79] op_sel_hi:[1,0,1]
	v_pk_fma_f32 v[156:157], v[74:75], v[222:223], v[76:77] op_sel_hi:[1,0,1]
	v_pk_fma_f32 v[74:75], v[84:85], v[220:221], v[136:137] op_sel:[0,1,0] neg_lo:[1,0,0] neg_hi:[1,0,0]
	v_pk_fma_f32 v[82:83], v[192:193], v[220:221], v[138:139] op_sel:[0,1,0]
	v_pk_fma_f32 v[158:159], v[74:75], v[222:223], v[64:65] op_sel_hi:[1,0,1]
	v_pk_fma_f32 v[154:155], v[82:83], v[222:223], v[66:67] op_sel_hi:[1,0,1]
	v_cvt_f32_u32_e32 v74, v210
	v_cvt_f32_u32_e32 v75, v208
	v_cvt_f32_i32_e32 v82, v211
	v_cvt_f32_i32_e32 v83, v209
	v_pk_fma_f32 v[190:191], v[94:95], v[222:223], v[68:69] op_sel_hi:[1,0,1]
	v_pk_fma_f32 v[74:75], v[74:75], s[88:89], v[82:83] op_sel_hi:[1,0,1]
	s_nop 0
	v_pk_mul_f32 v[74:75], v[74:75], s[94:95] op_sel_hi:[1,0]
	s_nop 0
	v_fma_f32 v82, -v75, v75, v74
	v_add_f32_e32 v82, 0x3727c5ac, v82
	v_rsq_f32_e32 v82, v82
	v_pk_fma_f32 v[86:87], v[92:93], v[74:75], v[148:149] op_sel:[0,1,0] neg_lo:[1,0,0] neg_hi:[1,0,0]
	v_pk_fma_f32 v[94:95], v[198:199], v[74:75], v[150:151] op_sel:[0,1,0]
	v_pk_fma_f32 v[148:149], v[86:87], v[82:83], v[88:89] op_sel_hi:[1,0,1]
	v_pk_fma_f32 v[86:87], v[72:73], v[74:75], v[140:141] op_sel:[0,1,0] neg_lo:[1,0,0] neg_hi:[1,0,0]
	v_pk_fma_f32 v[144:145], v[94:95], v[82:83], v[90:91] op_sel_hi:[1,0,1]
	v_pk_fma_f32 v[94:95], v[196:197], v[74:75], v[142:143] op_sel:[0,1,0]
	v_pk_fma_f32 v[150:151], v[86:87], v[82:83], v[68:69] op_sel_hi:[1,0,1]
	v_pk_fma_f32 v[86:87], v[80:81], v[74:75], v[128:129] op_sel:[0,1,0] neg_lo:[1,0,0] neg_hi:[1,0,0]
	v_pk_fma_f32 v[146:147], v[94:95], v[82:83], v[70:71] op_sel_hi:[1,0,1]
	v_pk_fma_f32 v[94:95], v[194:195], v[74:75], v[130:131] op_sel:[0,1,0]
	v_pk_fma_f32 v[140:141], v[86:87], v[82:83], v[76:77] op_sel_hi:[1,0,1]
	v_pk_fma_f32 v[86:87], v[84:85], v[74:75], v[120:121] op_sel:[0,1,0] neg_lo:[1,0,0] neg_hi:[1,0,0]
	v_pk_fma_f32 v[74:75], v[192:193], v[74:75], v[122:123] op_sel:[0,1,0]
	v_pk_fma_f32 v[136:137], v[94:95], v[82:83], v[78:79] op_sel_hi:[1,0,1]
	v_pk_fma_f32 v[138:139], v[74:75], v[82:83], v[66:67] op_sel_hi:[1,0,1]
	v_pk_fma_f32 v[142:143], v[86:87], v[82:83], v[64:65] op_sel_hi:[1,0,1]
	v_cvt_f32_u32_e32 v74, v214
	v_cvt_f32_u32_e32 v75, v212
	v_cvt_f32_i32_e32 v82, v215
	v_cvt_f32_i32_e32 v83, v213
	v_pk_fma_f32 v[74:75], v[74:75], s[88:89], v[82:83] op_sel_hi:[1,0,1]
	s_nop 0
	v_pk_mul_f32 v[74:75], v[74:75], s[94:95] op_sel_hi:[1,0]
	s_nop 0
	v_fma_f32 v82, -v75, v75, v74
	v_add_f32_e32 v82, 0x3727c5ac, v82
	v_rsq_f32_e32 v82, v82
	v_pk_fma_f32 v[86:87], v[92:93], v[74:75], v[132:133] op_sel:[0,1,0] neg_lo:[1,0,0] neg_hi:[1,0,0]
	v_pk_fma_f32 v[94:95], v[198:199], v[74:75], v[134:135] op_sel:[0,1,0]
	v_pk_fma_f32 v[130:131], v[86:87], v[82:83], v[88:89] op_sel_hi:[1,0,1]
	v_pk_fma_f32 v[86:87], v[72:73], v[74:75], v[124:125] op_sel:[0,1,0] neg_lo:[1,0,0] neg_hi:[1,0,0]
	v_pk_fma_f32 v[128:129], v[94:95], v[82:83], v[90:91] op_sel_hi:[1,0,1]
	v_pk_fma_f32 v[94:95], v[196:197], v[74:75], v[126:127] op_sel:[0,1,0]
	v_pk_fma_f32 v[132:133], v[86:87], v[82:83], v[68:69] op_sel_hi:[1,0,1]
	v_pk_fma_f32 v[86:87], v[80:81], v[74:75], v[112:113] op_sel:[0,1,0] neg_lo:[1,0,0] neg_hi:[1,0,0]
	v_pk_fma_f32 v[126:127], v[94:95], v[82:83], v[70:71] op_sel_hi:[1,0,1]
	v_pk_fma_f32 v[94:95], v[194:195], v[74:75], v[114:115] op_sel:[0,1,0]
	v_pk_fma_f32 v[122:123], v[86:87], v[82:83], v[76:77] op_sel_hi:[1,0,1]
	v_pk_fma_f32 v[86:87], v[84:85], v[74:75], v[104:105] op_sel:[0,1,0] neg_lo:[1,0,0] neg_hi:[1,0,0]
	v_pk_fma_f32 v[74:75], v[192:193], v[74:75], v[106:107] op_sel:[0,1,0]
	v_pk_fma_f32 v[114:115], v[94:95], v[82:83], v[78:79] op_sel_hi:[1,0,1]
	v_pk_fma_f32 v[120:121], v[74:75], v[82:83], v[66:67] op_sel_hi:[1,0,1]
	v_pk_fma_f32 v[124:125], v[86:87], v[82:83], v[64:65] op_sel_hi:[1,0,1]
	v_cvt_f32_u32_e32 v74, v218
	v_cvt_f32_u32_e32 v75, v216
	v_cvt_f32_i32_e32 v82, v219
	v_cvt_f32_i32_e32 v83, v217
	v_pk_fma_f32 v[74:75], v[74:75], s[88:89], v[82:83] op_sel_hi:[1,0,1]
	s_nop 0
	v_pk_mul_f32 v[82:83], v[74:75], s[94:95] op_sel_hi:[1,0]
	s_nop 0
	v_fma_f32 v74, -v83, v83, v82
	v_add_f32_e32 v74, 0x3727c5ac, v74
	v_rsq_f32_e32 v94, v74
	v_pk_fma_f32 v[74:75], v[92:93], v[82:83], v[116:117] op_sel:[0,1,0] neg_lo:[1,0,0] neg_hi:[1,0,0]
	v_pk_fma_f32 v[86:87], v[198:199], v[82:83], v[118:119] op_sel:[0,1,0]
	v_pk_fma_f32 v[96:97], v[84:85], v[82:83], v[96:97] op_sel:[0,1,0] neg_lo:[1,0,0] neg_hi:[1,0,0]
	v_pk_fma_f32 v[104:105], v[86:87], v[94:95], v[90:91] op_sel_hi:[1,0,1]
	v_pk_fma_f32 v[112:113], v[74:75], v[94:95], v[88:89] op_sel_hi:[1,0,1]
	v_pk_fma_f32 v[74:75], v[72:73], v[82:83], v[108:109] op_sel:[0,1,0] neg_lo:[1,0,0] neg_hi:[1,0,0]
	v_pk_fma_f32 v[86:87], v[196:197], v[82:83], v[110:111] op_sel:[0,1,0]
	v_pk_fma_f32 v[108:109], v[74:75], v[94:95], v[68:69] op_sel_hi:[1,0,1]
	v_pk_fma_f32 v[106:107], v[86:87], v[94:95], v[70:71] op_sel_hi:[1,0,1]
	v_pk_fma_f32 v[86:87], v[80:81], v[82:83], v[100:101] op_sel:[0,1,0] neg_lo:[1,0,0] neg_hi:[1,0,0]
	v_pk_fma_f32 v[74:75], v[194:195], v[82:83], v[102:103] op_sel:[0,1,0]
	v_pk_fma_f32 v[82:83], v[192:193], v[82:83], v[98:99] op_sel:[0,1,0]
	v_pk_fma_f32 v[74:75], v[74:75], v[94:95], v[78:79] op_sel_hi:[1,0,1]
	v_pk_fma_f32 v[86:87], v[86:87], v[94:95], v[76:77] op_sel_hi:[1,0,1]
	v_pk_fma_f32 v[82:83], v[82:83], v[94:95], v[66:67] op_sel_hi:[1,0,1]
	v_pk_fma_f32 v[94:95], v[96:97], v[94:95], v[64:65] op_sel_hi:[1,0,1]
	global_load_dwordx2 v[102:103], v[202:203], off offset:1024
	global_load_dwordx2 v[110:111], v[200:201], off offset:1024
	global_load_dwordx2 v[98:99], v[202:203], off offset:1152
	global_load_dwordx2 v[100:101], v[200:201], off offset:1152
	global_load_dwordx2 v[96:97], v[202:203], off offset:1280
	global_load_dwordx2 v[118:119], v[200:201], off offset:1280
	global_load_dwordx2 v[116:117], v[202:203], off offset:1408
	global_load_dwordx2 v[134:135], v[200:201], off offset:1408
	s_waitcnt vmcnt(0)
	v_cvt_f32_u32_e32 v201, v102
	v_cvt_f32_u32_e32 v200, v110
	v_cvt_f32_i32_e32 v102, v111
	v_cvt_f32_i32_e32 v103, v103
	v_cvt_f32_i32_e32 v99, v99
	v_cvt_f32_i32_e32 v97, v97
	v_pk_fma_f32 v[102:103], v[200:201], s[88:89], v[102:103] op_sel_hi:[1,0,1]
	s_nop 0
	v_pk_mul_f32 v[102:103], v[102:103], s[94:95] op_sel_hi:[1,0]
	s_nop 0
	v_fma_f32 v110, -v103, v103, v102
	v_add_f32_e32 v110, 0x3727c5ac, v110
	v_rsq_f32_e32 v110, v110
	v_pk_fma_f32 v[200:201], v[92:93], v[102:103], v[60:61] op_sel:[0,1,0] neg_lo:[1,0,0] neg_hi:[1,0,0]
	v_pk_fma_f32 v[60:61], v[198:199], v[102:103], v[62:63] op_sel:[0,1,0]
	v_pk_fma_f32 v[62:63], v[200:201], v[110:111], v[88:89] op_sel_hi:[1,0,1]
	v_pk_fma_f32 v[200:201], v[72:73], v[102:103], v[56:57] op_sel:[0,1,0] neg_lo:[1,0,0] neg_hi:[1,0,0]
	v_pk_fma_f32 v[56:57], v[196:197], v[102:103], v[58:59] op_sel:[0,1,0]
	v_pk_fma_f32 v[58:59], v[200:201], v[110:111], v[68:69] op_sel_hi:[1,0,1]
	v_pk_fma_f32 v[200:201], v[80:81], v[102:103], v[52:53] op_sel:[0,1,0] neg_lo:[1,0,0] neg_hi:[1,0,0]
	v_pk_fma_f32 v[52:53], v[194:195], v[102:103], v[54:55] op_sel:[0,1,0]
	v_pk_fma_f32 v[54:55], v[200:201], v[110:111], v[76:77] op_sel_hi:[1,0,1]
	v_pk_fma_f32 v[200:201], v[84:85], v[102:103], v[48:49] op_sel:[0,1,0] neg_lo:[1,0,0] neg_hi:[1,0,0]
	v_pk_fma_f32 v[48:49], v[192:193], v[102:103], v[50:51] op_sel:[0,1,0]
	v_cvt_f32_u32_e32 v102, v100
	v_cvt_f32_u32_e32 v103, v98
	v_cvt_f32_i32_e32 v98, v101
	v_pk_fma_f32 v[48:49], v[48:49], v[110:111], v[66:67] op_sel_hi:[1,0,1]
	v_pk_fma_f32 v[56:57], v[56:57], v[110:111], v[70:71] op_sel_hi:[1,0,1]
	v_pk_fma_f32 v[50:51], v[200:201], v[110:111], v[64:65] op_sel_hi:[1,0,1]
	v_pk_fma_f32 v[98:99], v[102:103], s[88:89], v[98:99] op_sel_hi:[1,0,1]
	v_pk_fma_f32 v[52:53], v[52:53], v[110:111], v[78:79] op_sel_hi:[1,0,1]
	v_pk_mul_f32 v[98:99], v[98:99], s[94:95] op_sel_hi:[1,0]
	v_pk_fma_f32 v[60:61], v[60:61], v[110:111], v[90:91] op_sel_hi:[1,0,1]
	v_fma_f32 v100, -v99, v99, v98
	v_add_f32_e32 v100, 0x3727c5ac, v100
	v_rsq_f32_e32 v100, v100
	v_pk_fma_f32 v[102:103], v[92:93], v[98:99], v[44:45] op_sel:[0,1,0] neg_lo:[1,0,0] neg_hi:[1,0,0]
	v_pk_fma_f32 v[44:45], v[198:199], v[98:99], v[46:47] op_sel:[0,1,0]
	v_max_f32_e32 v56, 0, v56
	v_pk_fma_f32 v[46:47], v[102:103], v[100:101], v[88:89] op_sel_hi:[1,0,1]
	v_pk_fma_f32 v[102:103], v[72:73], v[98:99], v[40:41] op_sel:[0,1,0] neg_lo:[1,0,0] neg_hi:[1,0,0]
	v_pk_fma_f32 v[40:41], v[196:197], v[98:99], v[42:43] op_sel:[0,1,0]
	v_pk_fma_f32 v[42:43], v[102:103], v[100:101], v[68:69] op_sel_hi:[1,0,1]
	v_pk_fma_f32 v[102:103], v[80:81], v[98:99], v[36:37] op_sel:[0,1,0] neg_lo:[1,0,0] neg_hi:[1,0,0]
	v_pk_fma_f32 v[36:37], v[194:195], v[98:99], v[38:39] op_sel:[0,1,0]
	v_pk_fma_f32 v[38:39], v[102:103], v[100:101], v[76:77] op_sel_hi:[1,0,1]
	v_pk_fma_f32 v[102:103], v[84:85], v[98:99], v[32:33] op_sel:[0,1,0] neg_lo:[1,0,0] neg_hi:[1,0,0]
	v_pk_fma_f32 v[32:33], v[192:193], v[98:99], v[34:35] op_sel:[0,1,0]
	v_cvt_f32_u32_e32 v98, v118
	v_cvt_f32_u32_e32 v99, v96
	v_cvt_f32_i32_e32 v96, v119
	v_pk_fma_f32 v[44:45], v[44:45], v[100:101], v[90:91] op_sel_hi:[1,0,1]
	v_pk_fma_f32 v[40:41], v[40:41], v[100:101], v[70:71] op_sel_hi:[1,0,1]
	v_pk_fma_f32 v[36:37], v[36:37], v[100:101], v[78:79] op_sel_hi:[1,0,1]
	v_pk_fma_f32 v[96:97], v[98:99], s[88:89], v[96:97] op_sel_hi:[1,0,1]
	v_pk_fma_f32 v[32:33], v[32:33], v[100:101], v[66:67] op_sel_hi:[1,0,1]
	v_pk_mul_f32 v[96:97], v[96:97], s[94:95] op_sel_hi:[1,0]
	v_pk_fma_f32 v[34:35], v[102:103], v[100:101], v[64:65] op_sel_hi:[1,0,1]
	v_fma_f32 v98, -v97, v97, v96
	v_add_f32_e32 v98, 0x3727c5ac, v98
	v_rsq_f32_e32 v98, v98
	v_pk_fma_f32 v[100:101], v[92:93], v[96:97], v[28:29] op_sel:[0,1,0] neg_lo:[1,0,0] neg_hi:[1,0,0]
	v_pk_fma_f32 v[28:29], v[198:199], v[96:97], v[30:31] op_sel:[0,1,0]
	v_max_f32_e32 v60, 0, v60
	v_pk_fma_f32 v[30:31], v[100:101], v[98:99], v[88:89] op_sel_hi:[1,0,1]
	v_pk_fma_f32 v[100:101], v[72:73], v[96:97], v[24:25] op_sel:[0,1,0] neg_lo:[1,0,0] neg_hi:[1,0,0]
	v_pk_fma_f32 v[24:25], v[196:197], v[96:97], v[26:27] op_sel:[0,1,0]
	v_pk_fma_f32 v[26:27], v[100:101], v[98:99], v[68:69] op_sel_hi:[1,0,1]
	v_pk_fma_f32 v[100:101], v[80:81], v[96:97], v[20:21] op_sel:[0,1,0] neg_lo:[1,0,0] neg_hi:[1,0,0]
	v_pk_fma_f32 v[20:21], v[194:195], v[96:97], v[22:23] op_sel:[0,1,0]
	v_pk_fma_f32 v[22:23], v[100:101], v[98:99], v[76:77] op_sel_hi:[1,0,1]
	v_pk_fma_f32 v[100:101], v[84:85], v[96:97], v[16:17] op_sel:[0,1,0] neg_lo:[1,0,0] neg_hi:[1,0,0]
	v_pk_fma_f32 v[16:17], v[192:193], v[96:97], v[18:19] op_sel:[0,1,0]
	v_pk_fma_f32 v[28:29], v[28:29], v[98:99], v[90:91] op_sel_hi:[1,0,1]
	v_pk_fma_f32 v[24:25], v[24:25], v[98:99], v[70:71] op_sel_hi:[1,0,1]
	v_pk_fma_f32 v[20:21], v[20:21], v[98:99], v[78:79] op_sel_hi:[1,0,1]
	v_pk_fma_f32 v[16:17], v[16:17], v[98:99], v[66:67] op_sel_hi:[1,0,1]
	v_pk_fma_f32 v[18:19], v[100:101], v[98:99], v[64:65] op_sel_hi:[1,0,1]
	v_cvt_f32_u32_e32 v96, v134
	v_cvt_f32_u32_e32 v97, v116
	v_cvt_f32_i32_e32 v98, v135
	v_cvt_f32_i32_e32 v99, v117
	v_max_f32_e32 v62, 0, v62
	v_max_f32_e32 v63, 0, v63
	v_mul_f32_e32 v60, v60, v60
	v_pk_fma_f32 v[96:97], v[96:97], s[88:89], v[98:99] op_sel_hi:[1,0,1]
	v_max_f32_e32 v57, 0, v57
	v_pk_mul_f32 v[96:97], v[96:97], s[94:95] op_sel_hi:[1,0]
	v_mul_f32_e32 v62, v62, v62
	v_fma_f32 v98, -v97, v97, v96
	v_add_f32_e32 v98, 0x3727c5ac, v98
	v_rsq_f32_e32 v98, v98
	v_pk_fma_f32 v[72:73], v[72:73], v[96:97], v[8:9] op_sel:[0,1,0] neg_lo:[1,0,0] neg_hi:[1,0,0]
	v_pk_fma_f32 v[8:9], v[196:197], v[96:97], v[10:11] op_sel:[0,1,0]
	v_mul_f32_e32 v63, v63, v63
	v_pk_fma_f32 v[10:11], v[72:73], v[98:99], v[68:69] op_sel_hi:[1,0,1]
	v_pk_fma_f32 v[68:69], v[80:81], v[96:97], v[4:5] op_sel:[0,1,0] neg_lo:[1,0,0] neg_hi:[1,0,0]
	v_pk_fma_f32 v[4:5], v[194:195], v[96:97], v[6:7] op_sel:[0,1,0]
	v_pk_fma_f32 v[6:7], v[68:69], v[98:99], v[76:77] op_sel_hi:[1,0,1]
	v_pk_fma_f32 v[68:69], v[84:85], v[96:97], v[0:1] op_sel:[0,1,0] neg_lo:[1,0,0] neg_hi:[1,0,0]
	v_pk_fma_f32 v[0:1], v[192:193], v[96:97], v[2:3] op_sel:[0,1,0]
	v_pk_fma_f32 v[8:9], v[8:9], v[98:99], v[70:71] op_sel_hi:[1,0,1]
	v_pk_fma_f32 v[0:1], v[0:1], v[98:99], v[66:67] op_sel_hi:[1,0,1]
	v_max_f32_e32 v67, 0, v190
	v_pk_fma_f32 v[2:3], v[68:69], v[98:99], v[64:65] op_sel_hi:[1,0,1]
	v_max_f32_e32 v66, 0, v188
	v_mul_f32_e32 v68, v67, v67
	v_max_f32_e32 v67, 0, v189
	v_max_f32_e32 v69, 0, v191
	v_max_f32_e32 v70, 0, v184
	v_max_f32_e32 v71, 0, v186
	v_lshlrev_b64 v[64:65], 14, v[180:181]
	v_mul_f32_e32 v66, v66, v66
	v_mul_f32_e32 v67, v67, v67
	v_mul_f32_e32 v69, v69, v69
	v_mul_f32_e32 v70, v70, v70
	v_mul_f32_e32 v71, v71, v71
	v_max_f32_e32 v72, 0, v185
	v_max_f32_e32 v73, 0, v187
	v_mul_f32_e32 v72, v72, v72
	v_mul_f32_e32 v73, v73, v73
	v_cvt_pk_bf16_f32 v66, v66, v67
	v_cvt_pk_bf16_f32 v67, v70, v72
	v_cvt_pk_bf16_f32 v68, v68, v69
	v_cvt_pk_bf16_f32 v69, v71, v73
	v_lshl_add_u64 v[64:65], s[36:37], 0, v[64:65]
	v_lshlrev_b64 v[70:71], 1, v[182:183]
	v_lshl_add_u64 v[64:65], v[64:65], 0, v[70:71]
	global_store_dwordx4 v[64:65], v[66:69], off nt
	v_max_f32_e32 v72, 0, v152
	v_max_f32_e32 v73, 0, v154
	v_max_f32_e32 v66, 0, v156
	v_max_f32_e32 v67, 0, v158
	v_mul_f32_e32 v66, v66, v66
	v_mul_f32_e32 v68, v67, v67
	v_max_f32_e32 v67, 0, v157
	v_max_f32_e32 v69, 0, v159
	v_mul_f32_e32 v67, v67, v67
	v_mul_f32_e32 v69, v69, v69
	v_max_f32_e32 v76, 0, v153
	v_max_f32_e32 v77, 0, v155
	v_cvt_pk_bf16_f32 v66, v66, v67
	v_mul_f32_e32 v72, v72, v72
	v_mul_f32_e32 v73, v73, v73
	v_mul_f32_e32 v76, v76, v76
	v_mul_f32_e32 v77, v77, v77
	v_cvt_pk_bf16_f32 v67, v72, v76
	v_cvt_pk_bf16_f32 v68, v68, v69
	v_cvt_pk_bf16_f32 v69, v73, v77
	global_store_dwordx4 v[64:65], v[66:69], off offset:256 nt
	v_pk_fma_f32 v[4:5], v[4:5], v[98:99], v[78:79] op_sel_hi:[1,0,1]
	v_max_f32_e32 v76, 0, v144
	v_or_b32_e32 v66, 16, v180
	v_ashrrev_i32_e32 v67, 31, v66
	v_lshlrev_b64 v[72:73], 14, v[66:67]
	v_max_f32_e32 v67, 0, v150
	v_max_f32_e32 v66, 0, v148
	v_mul_f32_e32 v68, v67, v67
	v_max_f32_e32 v67, 0, v149
	v_mul_f32_e32 v66, v66, v66
	v_max_f32_e32 v69, 0, v151
	v_mul_f32_e32 v67, v67, v67
	v_max_f32_e32 v78, 0, v145
	v_lshl_add_u64 v[72:73], s[36:37], 0, v[72:73]
	v_mul_f32_e32 v69, v69, v69
	v_max_f32_e32 v77, 0, v146
	v_mul_f32_e32 v76, v76, v76
	v_max_f32_e32 v79, 0, v147
	v_mul_f32_e32 v78, v78, v78
	v_cvt_pk_bf16_f32 v66, v66, v67
	v_cvt_pk_bf16_f32 v67, v76, v78
	v_lshl_add_u64 v[72:73], v[72:73], 0, v[70:71]
	v_mul_f32_e32 v77, v77, v77
	v_mul_f32_e32 v79, v79, v79
	v_cvt_pk_bf16_f32 v68, v68, v69
	v_cvt_pk_bf16_f32 v69, v77, v79
	global_store_dwordx4 v[72:73], v[66:69], off nt
	v_max_f32_e32 v76, 0, v136
	v_max_f32_e32 v77, 0, v138
	v_max_f32_e32 v66, 0, v140
	v_max_f32_e32 v67, 0, v142
	v_mul_f32_e32 v66, v66, v66
	v_mul_f32_e32 v68, v67, v67
	v_max_f32_e32 v67, 0, v141
	v_max_f32_e32 v69, 0, v143
	v_mul_f32_e32 v67, v67, v67
	v_mul_f32_e32 v69, v69, v69
	v_max_f32_e32 v78, 0, v137
	v_max_f32_e32 v79, 0, v139
	v_cvt_pk_bf16_f32 v66, v66, v67
	v_mul_f32_e32 v76, v76, v76
	v_mul_f32_e32 v77, v77, v77
	v_mul_f32_e32 v78, v78, v78
	v_mul_f32_e32 v79, v79, v79
	v_cvt_pk_bf16_f32 v67, v76, v78
	v_cvt_pk_bf16_f32 v68, v68, v69
	v_cvt_pk_bf16_f32 v69, v77, v79
	global_store_dwordx4 v[72:73], v[66:69], off offset:256 nt
	v_max_f32_e32 v76, 0, v128
	v_max_f32_e32 v78, 0, v129
	v_or_b32_e32 v66, 32, v180
	v_ashrrev_i32_e32 v67, 31, v66
	v_lshlrev_b64 v[72:73], 14, v[66:67]
	v_max_f32_e32 v67, 0, v132
	v_max_f32_e32 v66, 0, v130
	v_mul_f32_e32 v68, v67, v67
	v_max_f32_e32 v67, 0, v131
	v_mul_f32_e32 v66, v66, v66
	v_max_f32_e32 v69, 0, v133
	v_mul_f32_e32 v67, v67, v67
	v_lshl_add_u64 v[72:73], s[36:37], 0, v[72:73]
	v_mul_f32_e32 v69, v69, v69
	v_max_f32_e32 v77, 0, v126
	v_mul_f32_e32 v76, v76, v76
	v_max_f32_e32 v79, 0, v127
	v_mul_f32_e32 v78, v78, v78
	v_cvt_pk_bf16_f32 v66, v66, v67
	v_cvt_pk_bf16_f32 v67, v76, v78
	v_lshl_add_u64 v[72:73], v[72:73], 0, v[70:71]
	v_mul_f32_e32 v77, v77, v77
	v_mul_f32_e32 v79, v79, v79
	v_cvt_pk_bf16_f32 v68, v68, v69
	v_cvt_pk_bf16_f32 v69, v77, v79
	global_store_dwordx4 v[72:73], v[66:69], off nt
	v_max_f32_e32 v76, 0, v114
	v_max_f32_e32 v77, 0, v120
	v_max_f32_e32 v66, 0, v122
	v_max_f32_e32 v67, 0, v124
	v_mul_f32_e32 v66, v66, v66
	v_mul_f32_e32 v68, v67, v67
	v_max_f32_e32 v67, 0, v123
	v_max_f32_e32 v69, 0, v125
	v_mul_f32_e32 v67, v67, v67
	v_mul_f32_e32 v69, v69, v69
	v_max_f32_e32 v78, 0, v115
	v_max_f32_e32 v79, 0, v121
	v_cvt_pk_bf16_f32 v66, v66, v67
	v_mul_f32_e32 v76, v76, v76
	v_mul_f32_e32 v77, v77, v77
	v_mul_f32_e32 v78, v78, v78
	v_mul_f32_e32 v79, v79, v79
	v_cvt_pk_bf16_f32 v67, v76, v78
	v_cvt_pk_bf16_f32 v68, v68, v69
	v_cvt_pk_bf16_f32 v69, v77, v79
	global_store_dwordx4 v[72:73], v[66:69], off offset:256 nt
	v_max_f32_e32 v76, 0, v104
	v_max_f32_e32 v78, 0, v105
	v_or_b32_e32 v66, 48, v180
	v_ashrrev_i32_e32 v67, 31, v66
	v_lshlrev_b64 v[72:73], 14, v[66:67]
	v_max_f32_e32 v67, 0, v108
	v_max_f32_e32 v66, 0, v112
	v_mul_f32_e32 v68, v67, v67
	v_max_f32_e32 v67, 0, v113
	v_mul_f32_e32 v66, v66, v66
	v_max_f32_e32 v69, 0, v109
	v_mul_f32_e32 v67, v67, v67
	v_lshl_add_u64 v[72:73], s[36:37], 0, v[72:73]
	v_mul_f32_e32 v69, v69, v69
	v_max_f32_e32 v77, 0, v106
	v_mul_f32_e32 v76, v76, v76
	v_max_f32_e32 v79, 0, v107
	v_mul_f32_e32 v78, v78, v78
	v_cvt_pk_bf16_f32 v66, v66, v67
	v_cvt_pk_bf16_f32 v67, v76, v78
	v_lshl_add_u64 v[70:71], v[72:73], 0, v[70:71]
	v_mul_f32_e32 v77, v77, v77
	v_mul_f32_e32 v79, v79, v79
	v_cvt_pk_bf16_f32 v68, v68, v69
	v_cvt_pk_bf16_f32 v69, v77, v79
	global_store_dwordx4 v[70:71], v[66:69], off nt
	v_max_f32_e32 v72, 0, v74
	v_max_f32_e32 v73, 0, v82
	v_max_f32_e32 v66, 0, v86
	v_max_f32_e32 v67, 0, v94
	v_mul_f32_e32 v66, v66, v66
	v_mul_f32_e32 v68, v67, v67
	v_max_f32_e32 v67, 0, v87
	v_max_f32_e32 v69, 0, v95
	v_mul_f32_e32 v67, v67, v67
	v_mul_f32_e32 v69, v69, v69
	v_max_f32_e32 v74, 0, v75
	v_max_f32_e32 v75, 0, v83
	v_cvt_pk_bf16_f32 v66, v66, v67
	v_mul_f32_e32 v72, v72, v72
	v_mul_f32_e32 v73, v73, v73
	v_mul_f32_e32 v74, v74, v74
	v_mul_f32_e32 v75, v75, v75
	v_cvt_pk_bf16_f32 v67, v72, v74
	v_cvt_pk_bf16_f32 v68, v68, v69
	v_cvt_pk_bf16_f32 v69, v73, v75
	global_store_dwordx4 v[70:71], v[66:69], off offset:256 nt
	v_max_f32_e32 v58, 0, v58
	v_max_f32_e32 v59, 0, v59
	v_mul_f32_e32 v66, v56, v56
	v_max_f32_e32 v56, 0, v61
	v_mul_f32_e32 v61, v56, v56
	v_mul_f32_e32 v67, v57, v57
	v_cvt_pk_bf16_f32 v56, v62, v63
	v_cvt_pk_bf16_f32 v57, v60, v61
	v_lshl_add_u64 v[60:61], v[64:65], 0, s[0:1]
	s_mov_b32 s0, 0x200000
	v_add_co_u32_e32 v62, vcc, s0, v64
	v_mul_f32_e32 v58, v58, v58
	v_mul_f32_e32 v59, v59, v59
	v_addc_co_u32_e32 v63, vcc, 0, v65, vcc
	v_max_f32_e32 v48, 0, v48
	v_cvt_pk_bf16_f32 v58, v58, v59
	v_cvt_pk_bf16_f32 v59, v66, v67
	global_store_dwordx4 v[62:63], v[56:59], off nt
	v_max_f32_e32 v54, 0, v54
	v_max_f32_e32 v50, 0, v50
	v_max_f32_e32 v55, 0, v55
	v_max_f32_e32 v51, 0, v51
	v_mul_f32_e32 v56, v48, v48
	v_max_f32_e32 v48, 0, v53
	v_mul_f32_e32 v54, v54, v54
	v_mul_f32_e32 v50, v50, v50
	v_mul_f32_e32 v55, v55, v55
	v_mul_f32_e32 v51, v51, v51
	v_max_f32_e32 v52, 0, v52
	v_max_f32_e32 v49, 0, v49
	v_mul_f32_e32 v53, v48, v48
	v_cvt_pk_bf16_f32 v48, v54, v55
	v_max_f32_e32 v40, 0, v40
	v_mul_f32_e32 v52, v52, v52
	v_mul_f32_e32 v57, v49, v49
	v_cvt_pk_bf16_f32 v49, v52, v53
	v_cvt_pk_bf16_f32 v50, v50, v51
	v_cvt_pk_bf16_f32 v51, v56, v57
	global_store_dwordx4 v[60:61], v[48:51], off offset:256 nt
	v_max_f32_e32 v44, 0, v44
	v_max_f32_e32 v46, 0, v46
	v_mul_f32_e32 v48, v40, v40
	v_max_f32_e32 v40, 0, v45
	v_max_f32_e32 v47, 0, v47
	v_mul_f32_e32 v44, v44, v44
	v_max_f32_e32 v41, 0, v41
	v_mul_f32_e32 v45, v40, v40
	s_mov_b64 s[0:1], 0x240000
	v_mul_f32_e32 v46, v46, v46
	v_mul_f32_e32 v47, v47, v47
	v_mul_f32_e32 v49, v41, v41
	v_cvt_pk_bf16_f32 v40, v46, v47
	v_cvt_pk_bf16_f32 v41, v44, v45
	v_lshl_add_u64 v[44:45], v[64:65], 0, s[0:1]
	s_mov_b32 s0, 0x240000
	v_max_f32_e32 v42, 0, v42
	v_max_f32_e32 v43, 0, v43
	v_add_co_u32_e32 v46, vcc, s0, v64
	v_mul_f32_e32 v42, v42, v42
	v_mul_f32_e32 v43, v43, v43
	v_addc_co_u32_e32 v47, vcc, 0, v65, vcc
	v_max_f32_e32 v32, 0, v32
	v_cvt_pk_bf16_f32 v42, v42, v43
	v_cvt_pk_bf16_f32 v43, v48, v49
	global_store_dwordx4 v[46:47], v[40:43], off nt
	v_max_f32_e32 v38, 0, v38
	v_max_f32_e32 v34, 0, v34
	v_max_f32_e32 v39, 0, v39
	v_max_f32_e32 v35, 0, v35
	v_mul_f32_e32 v40, v32, v32
	v_max_f32_e32 v32, 0, v37
	v_mul_f32_e32 v38, v38, v38
	v_mul_f32_e32 v34, v34, v34
	v_mul_f32_e32 v39, v39, v39
	v_mul_f32_e32 v35, v35, v35
	v_max_f32_e32 v36, 0, v36
	v_max_f32_e32 v33, 0, v33
	v_mul_f32_e32 v37, v32, v32
	v_cvt_pk_bf16_f32 v32, v38, v39
	v_max_f32_e32 v24, 0, v24
	v_mul_f32_e32 v36, v36, v36
	v_mul_f32_e32 v41, v33, v33
	v_cvt_pk_bf16_f32 v33, v36, v37
	v_cvt_pk_bf16_f32 v34, v34, v35
	v_cvt_pk_bf16_f32 v35, v40, v41
	global_store_dwordx4 v[44:45], v[32:35], off offset:256 nt
	v_max_f32_e32 v28, 0, v28
	v_max_f32_e32 v30, 0, v30
	v_mul_f32_e32 v32, v24, v24
	v_max_f32_e32 v24, 0, v29
	v_max_f32_e32 v31, 0, v31
	v_mul_f32_e32 v28, v28, v28
	v_max_f32_e32 v25, 0, v25
	v_mul_f32_e32 v29, v24, v24
	s_mov_b64 s[0:1], 0x280000
	v_mul_f32_e32 v30, v30, v30
	v_mul_f32_e32 v31, v31, v31
	v_mul_f32_e32 v33, v25, v25
	v_cvt_pk_bf16_f32 v24, v30, v31
	v_cvt_pk_bf16_f32 v25, v28, v29
	v_lshl_add_u64 v[28:29], v[64:65], 0, s[0:1]
	s_mov_b32 s0, 0x280000
	v_max_f32_e32 v26, 0, v26
	v_max_f32_e32 v27, 0, v27
	v_add_co_u32_e32 v30, vcc, s0, v64
	v_mul_f32_e32 v26, v26, v26
	v_mul_f32_e32 v27, v27, v27
	v_addc_co_u32_e32 v31, vcc, 0, v65, vcc
	v_max_f32_e32 v16, 0, v16
	v_pk_fma_f32 v[92:93], v[92:93], v[96:97], v[12:13] op_sel:[0,1,0] neg_lo:[1,0,0] neg_hi:[1,0,0]
	v_pk_fma_f32 v[12:13], v[198:199], v[96:97], v[14:15] op_sel:[0,1,0]
	v_cvt_pk_bf16_f32 v26, v26, v27
	v_cvt_pk_bf16_f32 v27, v32, v33
	global_store_dwordx4 v[30:31], v[24:27], off nt
	v_max_f32_e32 v22, 0, v22
	v_max_f32_e32 v18, 0, v18
	v_max_f32_e32 v23, 0, v23
	v_max_f32_e32 v19, 0, v19
	v_mul_f32_e32 v24, v16, v16
	v_max_f32_e32 v16, 0, v21
	v_pk_fma_f32 v[12:13], v[12:13], v[98:99], v[90:91] op_sel_hi:[1,0,1]
	v_mul_f32_e32 v22, v22, v22
	v_mul_f32_e32 v18, v18, v18
	v_mul_f32_e32 v23, v23, v23
	v_mul_f32_e32 v19, v19, v19
	v_max_f32_e32 v20, 0, v20
	v_max_f32_e32 v17, 0, v17
	v_mul_f32_e32 v21, v16, v16
	v_cvt_pk_bf16_f32 v16, v22, v23
	v_max_f32_e32 v8, 0, v8
	v_pk_fma_f32 v[14:15], v[92:93], v[98:99], v[88:89] op_sel_hi:[1,0,1]
	v_mul_f32_e32 v20, v20, v20
	v_mul_f32_e32 v25, v17, v17
	v_cvt_pk_bf16_f32 v17, v20, v21
	v_cvt_pk_bf16_f32 v18, v18, v19
	v_cvt_pk_bf16_f32 v19, v24, v25
	global_store_dwordx4 v[28:29], v[16:19], off offset:256 nt
	v_max_f32_e32 v12, 0, v12
	v_max_f32_e32 v14, 0, v14
	v_mul_f32_e32 v16, v8, v8
	v_max_f32_e32 v8, 0, v13
	v_max_f32_e32 v15, 0, v15
	v_mul_f32_e32 v12, v12, v12
	v_max_f32_e32 v9, 0, v9
	v_mul_f32_e32 v13, v8, v8
	s_mov_b64 s[0:1], 0x2c0000
	v_mul_f32_e32 v14, v14, v14
	v_mul_f32_e32 v15, v15, v15
	v_mul_f32_e32 v17, v9, v9
	v_cvt_pk_bf16_f32 v8, v14, v15
	v_cvt_pk_bf16_f32 v9, v12, v13
	v_lshl_add_u64 v[12:13], v[64:65], 0, s[0:1]
	s_mov_b32 s0, 0x2c0000
	v_max_f32_e32 v10, 0, v10
	v_max_f32_e32 v11, 0, v11
	v_add_co_u32_e32 v14, vcc, s0, v64
	v_mul_f32_e32 v10, v10, v10
	v_mul_f32_e32 v11, v11, v11
	v_addc_co_u32_e32 v15, vcc, 0, v65, vcc
	v_max_f32_e32 v2, 0, v2
	v_max_f32_e32 v3, 0, v3
	v_max_f32_e32 v0, 0, v0
	v_cvt_pk_bf16_f32 v10, v10, v11
	v_cvt_pk_bf16_f32 v11, v16, v17
	global_store_dwordx4 v[14:15], v[8:11], off nt
	v_max_f32_e32 v6, 0, v6
	v_mul_f32_e32 v2, v2, v2
	v_max_f32_e32 v7, 0, v7
	v_mul_f32_e32 v3, v3, v3
	v_max_f32_e32 v4, 0, v4
	v_mul_f32_e32 v8, v0, v0
	v_max_f32_e32 v0, 0, v5
	v_max_f32_e32 v1, 0, v1
	s_and_b64 vcc, exec, s[6:7]
	s_mov_b64 s[0:1], s[76:77]
	v_mul_f32_e32 v6, v6, v6
	v_mul_f32_e32 v7, v7, v7
	v_mul_f32_e32 v4, v4, v4
	v_mul_f32_e32 v5, v0, v0
	v_mul_f32_e32 v9, v1, v1
	v_cvt_pk_bf16_f32 v0, v6, v7
	v_cvt_pk_bf16_f32 v1, v4, v5
	v_cvt_pk_bf16_f32 v2, v2, v3
	v_cvt_pk_bf16_f32 v3, v8, v9
	global_store_dwordx4 v[12:13], v[0:3], off offset:256 nt
	s_cbranch_vccz .LBB0_1049
	s_waitcnt vmcnt(0)
	v_readlane_b32 s38, v255, 9
	s_cmpk_gt_u32 s18, 0xff
	v_readlane_b32 s39, v255, 10
	s_cbranch_scc1 .LBB0_1060
	s_barrier
